# GEMM K-loops: single combined vmcnt+lgkmcnt wait per super-phase
# baseline (speedup 1.0000x reference)
; #define PG8_STAGE(bufoff, gbase, voff) do { _Pragma("unroll") for (int _i = 0; _i < 2; ++_i) \
;         __builtin_amdgcn_global_load_lds((const unsigned*)((const char*)(gbase) + (voff)[_i]), (PG8_LAS unsigned*)(lds + (bufoff) + ldsw + _i * 8192), 16, 0, 0); } while (0)
; #define PG8_LDA(dst, b, h) do { _Pragma("unroll") for (int m = 0; m < 4; ++m) _Pragma("unroll") for (int k = 0; k < 2; ++k) dst[m][k] = *(const PG8_LAS bf16x8*)(lds + PG8_SA(b, h) + aoff + m * 2048 + k * 1024); } while (0)
; #define PG8_LDB(dst, b, h) do { _Pragma("unroll") for (int n = 0; n < 2; ++n) _Pragma("unroll") for (int k = 0; k < 2; ++k) dst[n][k] = *(const PG8_LAS bf16x8*)(lds + PG8_SB(b, h) + boff + n * 2048 + k * 1024); } while (0)
; #define PG8_MMA(ai, bj, At, Bt) do { __builtin_amdgcn_s_setprio(1); _Pragma("unroll") for (int m = 0; m < 4; ++m) _Pragma("unroll") for (int n = 0; n < 2; ++n) _Pragma("unroll") for (int k = 0; k < 2; ++k) \
;         acc[ai][bj][m][n] = __builtin_amdgcn_mfma_f32_16x16x32_bf16(Bt[n][k], At[m][k], acc[ai][bj][m][n], 0, 0, 0); __builtin_amdgcn_s_setprio(0); } while (0)
; #define PG8_WAIT_V(n) asm volatile("s_waitcnt vmcnt(" #n ")" ::: "memory")
; #define PG8_WAIT_L(n) asm volatile("s_waitcnt lgkmcnt(" #n ")" ::: "memory")
; #define PG8_BAR __builtin_amdgcn_s_barrier()
; #define PG8_SCHED __builtin_amdgcn_sched_barrier(0)
; template <class Epi, class Sched, bool ALIGN_EPI = false, bool SP2 = false>
; __device__ __forceinline__ void gemm_phase(PG8_LAS unsigned char* lds, const Gemm g, const Sched& S, const Epi& E) {
;     ...
;             PG8_LDB(B0, 0, 0); PG8_LDB(B1, 0, 1); PG8_SCHED; PG8_LDA(At, 0, 0); PG8_STAGE(PG8_SA(1, 1), a1 + hstep, voffA);
;             PG8_WAIT_V(8); PG8_WAIT_L(0); PG8_BAR; PG8_MMA(0, 0, At, B0); PG8_MMA(0, 1, At, B1); PG8_BAR; PG8_SCHED;
;             PG8_LDA(At, 0, 1); PG8_STAGE(PG8_SB(0, 0), b2, voffB); PG8_STAGE(PG8_SB(0, 1), b2 + hstep, voffB); PG8_STAGE(PG8_SA(0, 0), a2, voffA);
;             PG8_WAIT_V(8); PG8_WAIT_L(0); PG8_BAR; PG8_MMA(1, 0, At, B0); PG8_MMA(1, 1, At, B1); PG8_BAR; PG8_SCHED;
.LBB0_114:
	s_add_u32 s20, s8, 0xfffc0080
	s_addc_u32 s21, s9, -1
	s_add_i32 s41, 0, 0x10000
	s_cmp_eq_u32 s40, 12
	s_cselect_b32 s35, s13, s21
	s_cselect_b32 s34, s22, s20
	v_add_u32_e32 v0, s41, v154
	s_cselect_b32 s31, s11, s39
	s_cselect_b32 s30, s23, s38
	s_add_i32 s20, 0, 0x14000
	ds_read_b128 v[158:161], v0
	ds_read_b128 v[162:165], v0 offset:1024
	ds_read_b128 v[166:169], v0 offset:2048
	ds_read_b128 v[170:173], v0 offset:3072
	v_add_u32_e32 v0, s20, v154
	ds_read_b128 v[174:177], v0
	ds_read_b128 v[178:181], v0 offset:1024
	ds_read_b128 v[182:185], v0 offset:2048
	ds_read_b128 v[186:189], v0 offset:3072
	s_add_i32 m0, s46, 0xc000
	ds_read_b128 v[190:193], v156
	ds_read_b128 v[194:197], v156 offset:1024
	ds_read_b128 v[206:209], v156 offset:2048
	ds_read_b128 v[210:213], v156 offset:3072
	ds_read_b128 v[214:217], v156 offset:4096
	ds_read_b128 v[218:221], v156 offset:5120
	ds_read_b128 v[222:225], v156 offset:6144
	ds_read_b128 v[226:229], v156 offset:7168
	global_load_lds_dwordx4 v146, s[8:9]
	s_add_i32 m0, s46, 0xe000
	s_nop 0
	global_load_lds_dwordx4 v148, s[8:9]
	s_waitcnt vmcnt(8) lgkmcnt(0)
	s_barrier
	s_setprio 1
	v_mfma_f32_16x16x32_bf16 v[126:129], v[158:161], v[190:193], v[126:129]
	v_mfma_f32_16x16x32_bf16 v[122:125], v[166:169], v[190:193], v[122:125]
	v_mfma_f32_16x16x32_bf16 v[114:117], v[158:161], v[206:209], v[114:117]
	v_mfma_f32_16x16x32_bf16 v[106:109], v[166:169], v[206:209], v[106:109]
	v_mfma_f32_16x16x32_bf16 v[98:101], v[158:161], v[214:217], v[98:101]
	v_mfma_f32_16x16x32_bf16 v[90:93], v[166:169], v[214:217], v[90:93]
	v_mfma_f32_16x16x32_bf16 v[82:85], v[158:161], v[222:225], v[82:85]
	v_mfma_f32_16x16x32_bf16 v[74:77], v[166:169], v[222:225], v[74:77]
	v_mfma_f32_16x16x32_bf16 v[126:129], v[162:165], v[194:197], v[126:129]
	v_mfma_f32_16x16x32_bf16 v[122:125], v[170:173], v[194:197], v[122:125]
	v_mfma_f32_16x16x32_bf16 v[114:117], v[162:165], v[210:213], v[114:117]
	v_mfma_f32_16x16x32_bf16 v[106:109], v[170:173], v[210:213], v[106:109]
	v_mfma_f32_16x16x32_bf16 v[98:101], v[162:165], v[218:221], v[98:101]
	v_mfma_f32_16x16x32_bf16 v[90:93], v[170:173], v[218:221], v[90:93]
	v_mfma_f32_16x16x32_bf16 v[82:85], v[162:165], v[226:229], v[82:85]
	v_mfma_f32_16x16x32_bf16 v[74:77], v[170:173], v[226:229], v[74:77]
	v_mfma_f32_16x16x32_bf16 v[118:121], v[174:177], v[190:193], v[118:121]
	v_mfma_f32_16x16x32_bf16 v[110:113], v[182:185], v[190:193], v[110:113]
	v_mfma_f32_16x16x32_bf16 v[102:105], v[174:177], v[206:209], v[102:105]
	v_mfma_f32_16x16x32_bf16 v[94:97], v[182:185], v[206:209], v[94:97]
	v_mfma_f32_16x16x32_bf16 v[86:89], v[174:177], v[214:217], v[86:89]
	v_mfma_f32_16x16x32_bf16 v[78:81], v[182:185], v[214:217], v[78:81]
	v_mfma_f32_16x16x32_bf16 v[70:73], v[174:177], v[222:225], v[70:73]
	v_mfma_f32_16x16x32_bf16 v[66:69], v[182:185], v[222:225], v[66:69]
	v_mfma_f32_16x16x32_bf16 v[118:121], v[178:181], v[194:197], v[118:121]
	v_mfma_f32_16x16x32_bf16 v[110:113], v[186:189], v[194:197], v[110:113]
	v_mfma_f32_16x16x32_bf16 v[102:105], v[178:181], v[210:213], v[102:105]
	v_mfma_f32_16x16x32_bf16 v[94:97], v[186:189], v[210:213], v[94:97]
	v_mfma_f32_16x16x32_bf16 v[86:89], v[178:181], v[218:221], v[86:89]
	v_mfma_f32_16x16x32_bf16 v[78:81], v[186:189], v[218:221], v[78:81]
	v_mfma_f32_16x16x32_bf16 v[70:73], v[178:181], v[226:229], v[70:73]
	v_mfma_f32_16x16x32_bf16 v[66:69], v[186:189], v[226:229], v[66:69]
	s_setprio 0
	s_barrier
	s_add_i32 s21, s41, s29
	s_mov_b32 m0, s21
	ds_read_b128 v[190:193], v156 offset:16384
	ds_read_b128 v[194:197], v156 offset:17408
	ds_read_b128 v[206:209], v156 offset:18432
	ds_read_b128 v[210:213], v156 offset:19456
	ds_read_b128 v[214:217], v156 offset:20480
	ds_read_b128 v[218:221], v156 offset:21504
	ds_read_b128 v[222:225], v156 offset:22528
	ds_read_b128 v[226:229], v156 offset:23552
	global_load_lds_dwordx4 v134, s[30:31]
	s_add_i32 m0, s21, 0x2000
	s_add_u32 s82, s30, 0x40000
	s_addc_u32 s83, s31, 0
	s_add_i32 s20, s20, s29
	global_load_lds_dwordx4 v130, s[30:31]
	s_mov_b32 m0, s20
	s_nop 0
	global_load_lds_dwordx4 v134, s[82:83]
	s_add_i32 m0, s20, 0x2000
	s_nop 0
	global_load_lds_dwordx4 v130, s[82:83]
	s_mov_b32 m0, s46
	s_nop 0
	global_load_lds_dwordx4 v136, s[34:35]
	s_mov_b32 m0, s47
	s_nop 0
	global_load_lds_dwordx4 v132, s[34:35]
	s_waitcnt vmcnt(8) lgkmcnt(0)
	s_barrier
	s_setprio 1
	v_mfma_f32_16x16x32_bf16 v[62:65], v[158:161], v[190:193], v[62:65]
	v_mfma_f32_16x16x32_bf16 v[58:61], v[166:169], v[190:193], v[58:61]
	v_mfma_f32_16x16x32_bf16 v[50:53], v[158:161], v[206:209], v[50:53]
	v_mfma_f32_16x16x32_bf16 v[42:45], v[166:169], v[206:209], v[42:45]
	v_mfma_f32_16x16x32_bf16 v[34:37], v[158:161], v[214:217], v[34:37]
	v_mfma_f32_16x16x32_bf16 v[26:29], v[166:169], v[214:217], v[26:29]
	v_mfma_f32_16x16x32_bf16 v[18:21], v[158:161], v[222:225], v[18:21]
	v_mfma_f32_16x16x32_bf16 v[10:13], v[166:169], v[222:225], v[10:13]
	v_mfma_f32_16x16x32_bf16 v[62:65], v[162:165], v[194:197], v[62:65]
	v_mfma_f32_16x16x32_bf16 v[58:61], v[170:173], v[194:197], v[58:61]
	v_mfma_f32_16x16x32_bf16 v[50:53], v[162:165], v[210:213], v[50:53]
	v_mfma_f32_16x16x32_bf16 v[42:45], v[170:173], v[210:213], v[42:45]
	v_mfma_f32_16x16x32_bf16 v[34:37], v[162:165], v[218:221], v[34:37]
	v_mfma_f32_16x16x32_bf16 v[26:29], v[170:173], v[218:221], v[26:29]
	v_mfma_f32_16x16x32_bf16 v[18:21], v[162:165], v[226:229], v[18:21]
	v_mfma_f32_16x16x32_bf16 v[10:13], v[170:173], v[226:229], v[10:13]
	v_mfma_f32_16x16x32_bf16 v[54:57], v[174:177], v[190:193], v[54:57]
	v_mfma_f32_16x16x32_bf16 v[46:49], v[182:185], v[190:193], v[46:49]
	v_mfma_f32_16x16x32_bf16 v[38:41], v[174:177], v[206:209], v[38:41]
	v_mfma_f32_16x16x32_bf16 v[30:33], v[182:185], v[206:209], v[30:33]
	v_mfma_f32_16x16x32_bf16 v[22:25], v[174:177], v[214:217], v[22:25]
	v_mfma_f32_16x16x32_bf16 v[14:17], v[182:185], v[214:217], v[14:17]
	v_mfma_f32_16x16x32_bf16 v[6:9], v[174:177], v[222:225], v[6:9]
	v_mfma_f32_16x16x32_bf16 v[2:5], v[182:185], v[222:225], v[2:5]
	v_mfma_f32_16x16x32_bf16 v[54:57], v[178:181], v[194:197], v[54:57]
	v_mfma_f32_16x16x32_bf16 v[46:49], v[186:189], v[194:197], v[46:49]
	v_mfma_f32_16x16x32_bf16 v[38:41], v[178:181], v[210:213], v[38:41]
	v_mfma_f32_16x16x32_bf16 v[30:33], v[186:189], v[210:213], v[30:33]
	v_mfma_f32_16x16x32_bf16 v[22:25], v[178:181], v[218:221], v[22:25]
	v_mfma_f32_16x16x32_bf16 v[14:17], v[186:189], v[218:221], v[14:17]
	v_mfma_f32_16x16x32_bf16 v[6:9], v[178:181], v[226:229], v[6:9]
	v_mfma_f32_16x16x32_bf16 v[2:5], v[186:189], v[226:229], v[2:5]
	s_setprio 0
	s_barrier
; #define PG8_STAGE(bufoff, gbase, voff) do { _Pragma("unroll") for (int _i = 0; _i < 2; ++_i) \
;         __builtin_amdgcn_global_load_lds((const unsigned*)((const char*)(gbase) + (voff)[_i]), (PG8_LAS unsigned*)(lds + (bufoff) + ldsw + _i * 8192), 16, 0, 0); } while (0)
; #define PG8_LDA(dst, b, h) do { _Pragma("unroll") for (int m = 0; m < 4; ++m) _Pragma("unroll") for (int k = 0; k < 2; ++k) dst[m][k] = *(const PG8_LAS bf16x8*)(lds + PG8_SA(b, h) + aoff + m * 2048 + k * 1024); } while (0)
; #define PG8_LDB(dst, b, h) do { _Pragma("unroll") for (int n = 0; n < 2; ++n) _Pragma("unroll") for (int k = 0; k < 2; ++k) dst[n][k] = *(const PG8_LAS bf16x8*)(lds + PG8_SB(b, h) + boff + n * 2048 + k * 1024); } while (0)
; #define PG8_MMA(ai, bj, At, Bt) do { __builtin_amdgcn_s_setprio(1); _Pragma("unroll") for (int m = 0; m < 4; ++m) _Pragma("unroll") for (int n = 0; n < 2; ++n) _Pragma("unroll") for (int k = 0; k < 2; ++k) \
;         acc[ai][bj][m][n] = __builtin_amdgcn_mfma_f32_16x16x32_bf16(Bt[n][k], At[m][k], acc[ai][bj][m][n], 0, 0, 0); __builtin_amdgcn_s_setprio(0); } while (0)
; #define PG8_WAIT_V(n) asm volatile("s_waitcnt vmcnt(" #n ")" ::: "memory")
; #define PG8_WAIT_L(n) asm volatile("s_waitcnt lgkmcnt(" #n ")" ::: "memory")
; #define PG8_BAR __builtin_amdgcn_s_barrier()
; #define PG8_SCHED __builtin_amdgcn_sched_barrier(0)
; template <class Epi, class Sched, bool ALIGN_EPI = false, bool SP2 = false>
; __device__ __forceinline__ void gemm_phase(PG8_LAS unsigned char* lds, const Gemm g, const Sched& S, const Epi& E) {
;     ...
;             PG8_LDB(B0, 1, 0); PG8_LDB(B1, 1, 1); PG8_SCHED; PG8_LDA(At, 1, 0); PG8_STAGE(PG8_SA(0, 1), a2 + hstep, voffA);
;             PG8_WAIT_V(8); PG8_WAIT_L(0); PG8_BAR; PG8_MMA(0, 0, At, B0); PG8_MMA(0, 1, At, B1); PG8_BAR; PG8_SCHED;
;             PG8_LDA(At, 1, 1); PG8_STAGE(PG8_SB(1, 0), b3, voffB); PG8_STAGE(PG8_SB(1, 1), b3 + hstep, voffB); PG8_STAGE(PG8_SA(1, 0), a3, voffA);
;             PG8_WAIT_V(8); PG8_WAIT_L(0); PG8_BAR; PG8_MMA(1, 0, At, B0); PG8_MMA(1, 1, At, B1); PG8_BAR; PG8_SCHED;
	s_add_i32 s20, 0, 0x18000
	v_add_u32_e32 v0, s20, v154
	s_add_i32 s21, 0, 0x1c000
	ds_read_b128 v[158:161], v0
	ds_read_b128 v[162:165], v0 offset:1024
	ds_read_b128 v[166:169], v0 offset:2048
	ds_read_b128 v[170:173], v0 offset:3072
	v_add_u32_e32 v0, s21, v154
	ds_read_b128 v[174:177], v0
	ds_read_b128 v[178:181], v0 offset:1024
	ds_read_b128 v[182:185], v0 offset:2048
	ds_read_b128 v[186:189], v0 offset:3072
	s_add_u32 vcc_lo, s34, 0x40000
	s_addc_u32 vcc_hi, s35, 0
	s_mov_b32 m0, s52
	ds_read_b128 v[190:193], v156 offset:32768
	ds_read_b128 v[194:197], v156 offset:33792
	ds_read_b128 v[206:209], v156 offset:34816
	ds_read_b128 v[210:213], v156 offset:35840
	ds_read_b128 v[214:217], v156 offset:36864
	ds_read_b128 v[218:221], v156 offset:37888
	ds_read_b128 v[222:225], v156 offset:38912
	ds_read_b128 v[226:229], v156 offset:39936
	global_load_lds_dwordx4 v136, vcc
	s_mov_b32 m0, s53
	s_nop 0
	global_load_lds_dwordx4 v132, vcc
	s_waitcnt vmcnt(8) lgkmcnt(0)
	s_barrier
	s_setprio 1
	v_mfma_f32_16x16x32_bf16 v[126:129], v[158:161], v[190:193], v[126:129]
	v_mfma_f32_16x16x32_bf16 v[122:125], v[166:169], v[190:193], v[122:125]
	v_mfma_f32_16x16x32_bf16 v[114:117], v[158:161], v[206:209], v[114:117]
	v_mfma_f32_16x16x32_bf16 v[106:109], v[166:169], v[206:209], v[106:109]
	v_mfma_f32_16x16x32_bf16 v[98:101], v[158:161], v[214:217], v[98:101]
	v_mfma_f32_16x16x32_bf16 v[90:93], v[166:169], v[214:217], v[90:93]
	v_mfma_f32_16x16x32_bf16 v[82:85], v[158:161], v[222:225], v[82:85]
	v_mfma_f32_16x16x32_bf16 v[74:77], v[166:169], v[222:225], v[74:77]
	v_mfma_f32_16x16x32_bf16 v[126:129], v[162:165], v[194:197], v[126:129]
	v_mfma_f32_16x16x32_bf16 v[122:125], v[170:173], v[194:197], v[122:125]
	v_mfma_f32_16x16x32_bf16 v[114:117], v[162:165], v[210:213], v[114:117]
	v_mfma_f32_16x16x32_bf16 v[106:109], v[170:173], v[210:213], v[106:109]
	v_mfma_f32_16x16x32_bf16 v[98:101], v[162:165], v[218:221], v[98:101]
	v_mfma_f32_16x16x32_bf16 v[90:93], v[170:173], v[218:221], v[90:93]
	v_mfma_f32_16x16x32_bf16 v[82:85], v[162:165], v[226:229], v[82:85]
	v_mfma_f32_16x16x32_bf16 v[74:77], v[170:173], v[226:229], v[74:77]
	v_mfma_f32_16x16x32_bf16 v[118:121], v[174:177], v[190:193], v[118:121]
	v_mfma_f32_16x16x32_bf16 v[110:113], v[182:185], v[190:193], v[110:113]
	v_mfma_f32_16x16x32_bf16 v[102:105], v[174:177], v[206:209], v[102:105]
	v_mfma_f32_16x16x32_bf16 v[94:97], v[182:185], v[206:209], v[94:97]
	v_mfma_f32_16x16x32_bf16 v[86:89], v[174:177], v[214:217], v[86:89]
	v_mfma_f32_16x16x32_bf16 v[78:81], v[182:185], v[214:217], v[78:81]
	v_mfma_f32_16x16x32_bf16 v[70:73], v[174:177], v[222:225], v[70:73]
	v_mfma_f32_16x16x32_bf16 v[66:69], v[182:185], v[222:225], v[66:69]
	v_mfma_f32_16x16x32_bf16 v[118:121], v[178:181], v[194:197], v[118:121]
	v_mfma_f32_16x16x32_bf16 v[110:113], v[186:189], v[194:197], v[110:113]
	v_mfma_f32_16x16x32_bf16 v[102:105], v[178:181], v[210:213], v[102:105]
	v_mfma_f32_16x16x32_bf16 v[94:97], v[186:189], v[210:213], v[94:97]
	v_mfma_f32_16x16x32_bf16 v[86:89], v[178:181], v[218:221], v[86:89]
	v_mfma_f32_16x16x32_bf16 v[78:81], v[186:189], v[218:221], v[78:81]
	v_mfma_f32_16x16x32_bf16 v[70:73], v[178:181], v[226:229], v[70:73]
	v_mfma_f32_16x16x32_bf16 v[66:69], v[186:189], v[226:229], v[66:69]
	s_setprio 0
	s_barrier
	s_add_i32 s20, s20, s29
	s_add_i32 m0, s20, 0xffffff80
	ds_read_b128 v[190:193], v156 offset:49152
	ds_read_b128 v[194:197], v156 offset:50176
	ds_read_b128 v[206:209], v156 offset:51200
	ds_read_b128 v[210:213], v156 offset:52224
	ds_read_b128 v[214:217], v156 offset:53248
	ds_read_b128 v[218:221], v156 offset:54272
	ds_read_b128 v[222:225], v156 offset:55296
	ds_read_b128 v[226:229], v156 offset:56320
	global_load_lds_dwordx4 v134, s[30:31] offset:128
	s_add_i32 m0, s20, 0x1f80
	s_add_i32 s20, s21, s29
	global_load_lds_dwordx4 v130, s[30:31] offset:128
	s_add_u32 s30, s30, 0x40080
	s_addc_u32 s31, s31, 0
	s_mov_b32 m0, s20
	s_nop 0
	global_load_lds_dwordx4 v134, s[30:31]
	s_add_i32 m0, s20, 0x2000
	s_nop 0
	global_load_lds_dwordx4 v130, s[30:31]
	s_add_i32 m0, s55, 0xffffff80
	s_nop 0
	global_load_lds_dwordx4 v136, s[34:35] offset:128
	s_add_i32 m0, s57, 0xffffff80
	s_nop 0
	global_load_lds_dwordx4 v132, s[34:35] offset:128
	s_waitcnt vmcnt(8) lgkmcnt(0)
	s_barrier
	s_setprio 1
	v_mfma_f32_16x16x32_bf16 v[62:65], v[158:161], v[190:193], v[62:65]
	v_mfma_f32_16x16x32_bf16 v[58:61], v[166:169], v[190:193], v[58:61]
	v_mfma_f32_16x16x32_bf16 v[50:53], v[158:161], v[206:209], v[50:53]
	v_mfma_f32_16x16x32_bf16 v[42:45], v[166:169], v[206:209], v[42:45]
	v_mfma_f32_16x16x32_bf16 v[34:37], v[158:161], v[214:217], v[34:37]
	v_mfma_f32_16x16x32_bf16 v[26:29], v[166:169], v[214:217], v[26:29]
	v_mfma_f32_16x16x32_bf16 v[18:21], v[158:161], v[222:225], v[18:21]
	v_mfma_f32_16x16x32_bf16 v[10:13], v[166:169], v[222:225], v[10:13]
	v_mfma_f32_16x16x32_bf16 v[62:65], v[162:165], v[194:197], v[62:65]
	v_mfma_f32_16x16x32_bf16 v[58:61], v[170:173], v[194:197], v[58:61]
	v_mfma_f32_16x16x32_bf16 v[50:53], v[162:165], v[210:213], v[50:53]
	v_mfma_f32_16x16x32_bf16 v[42:45], v[170:173], v[210:213], v[42:45]
	v_mfma_f32_16x16x32_bf16 v[34:37], v[162:165], v[218:221], v[34:37]
	v_mfma_f32_16x16x32_bf16 v[26:29], v[170:173], v[218:221], v[26:29]
	v_mfma_f32_16x16x32_bf16 v[18:21], v[162:165], v[226:229], v[18:21]
	v_mfma_f32_16x16x32_bf16 v[10:13], v[170:173], v[226:229], v[10:13]
	v_mfma_f32_16x16x32_bf16 v[54:57], v[174:177], v[190:193], v[54:57]
	v_mfma_f32_16x16x32_bf16 v[46:49], v[182:185], v[190:193], v[46:49]
	v_mfma_f32_16x16x32_bf16 v[38:41], v[174:177], v[206:209], v[38:41]
	v_mfma_f32_16x16x32_bf16 v[30:33], v[182:185], v[206:209], v[30:33]
	v_mfma_f32_16x16x32_bf16 v[22:25], v[174:177], v[214:217], v[22:25]
	v_mfma_f32_16x16x32_bf16 v[14:17], v[182:185], v[214:217], v[14:17]
	v_mfma_f32_16x16x32_bf16 v[6:9], v[174:177], v[222:225], v[6:9]
	v_mfma_f32_16x16x32_bf16 v[2:5], v[182:185], v[222:225], v[2:5]
	v_mfma_f32_16x16x32_bf16 v[54:57], v[178:181], v[194:197], v[54:57]
	v_mfma_f32_16x16x32_bf16 v[46:49], v[186:189], v[194:197], v[46:49]
	v_mfma_f32_16x16x32_bf16 v[38:41], v[178:181], v[210:213], v[38:41]
	v_mfma_f32_16x16x32_bf16 v[30:33], v[186:189], v[210:213], v[30:33]
	v_mfma_f32_16x16x32_bf16 v[22:25], v[178:181], v[218:221], v[22:25]
	v_mfma_f32_16x16x32_bf16 v[14:17], v[186:189], v[218:221], v[14:17]
	v_mfma_f32_16x16x32_bf16 v[6:9], v[178:181], v[226:229], v[6:9]
	v_mfma_f32_16x16x32_bf16 v[2:5], v[186:189], v[226:229], v[2:5]
	s_setprio 0
	s_barrier
	s_add_i32 s40, s40, 2
	s_add_u32 s8, s8, 0x100
	s_addc_u32 s9, s9, 0
	s_add_u32 s38, s38, 0x100
	s_addc_u32 s39, s39, 0
	s_cmp_gt_u32 s40, 13
	s_cbranch_scc0 .LBB0_114
	s_and_b64 vcc, exec, s[6:7]
	s_cbranch_vccz .LBB0_117
	s_barrier

; #define PG8_STAGE(bufoff, gbase, voff) do { _Pragma("unroll") for (int _i = 0; _i < 2; ++_i) \
;         __builtin_amdgcn_global_load_lds((const unsigned*)((const char*)(gbase) + (voff)[_i]), (PG8_LAS unsigned*)(lds + (bufoff) + ldsw + _i * 8192), 16, 0, 0); } while (0)
; #define PG8_LDA(dst, b, h) do { _Pragma("unroll") for (int m = 0; m < 4; ++m) _Pragma("unroll") for (int k = 0; k < 2; ++k) dst[m][k] = *(const PG8_LAS bf16x8*)(lds + PG8_SA(b, h) + aoff + m * 2048 + k * 1024); } while (0)
; #define PG8_LDB(dst, b, h) do { _Pragma("unroll") for (int n = 0; n < 2; ++n) _Pragma("unroll") for (int k = 0; k < 2; ++k) dst[n][k] = *(const PG8_LAS bf16x8*)(lds + PG8_SB(b, h) + boff + n * 2048 + k * 1024); } while (0)
; #define PG8_MMA(ai, bj, At, Bt) do { __builtin_amdgcn_s_setprio(1); _Pragma("unroll") for (int m = 0; m < 4; ++m) _Pragma("unroll") for (int n = 0; n < 2; ++n) _Pragma("unroll") for (int k = 0; k < 2; ++k) \
;         acc[ai][bj][m][n] = __builtin_amdgcn_mfma_f32_16x16x32_bf16(Bt[n][k], At[m][k], acc[ai][bj][m][n], 0, 0, 0); __builtin_amdgcn_s_setprio(0); } while (0)
; #define PG8_WAIT_V(n) asm volatile("s_waitcnt vmcnt(" #n ")" ::: "memory")
; #define PG8_WAIT_L(n) asm volatile("s_waitcnt lgkmcnt(" #n ")" ::: "memory")
; #define PG8_BAR __builtin_amdgcn_s_barrier()
; #define PG8_SCHED __builtin_amdgcn_sched_barrier(0)
; template <class Epi, class Sched, bool ALIGN_EPI = false, bool SP2 = false>
; __device__ __forceinline__ void gemm_phase(PG8_LAS unsigned char* lds, const Gemm g, const Sched& S, const Epi& E) {
;     ...
;             PG8_LDB(B0, 0, 0); PG8_LDB(B1, 0, 1); PG8_SCHED; PG8_LDA(At, 0, 0); PG8_STAGE(PG8_SA(1, 1), a1 + hstep, voffA);
;             PG8_WAIT_V(8); PG8_WAIT_L(0); PG8_BAR; PG8_MMA(0, 0, At, B0); PG8_MMA(0, 1, At, B1); PG8_BAR; PG8_SCHED;
;             PG8_LDA(At, 0, 1); PG8_STAGE(PG8_SB(0, 0), b2, voffB); PG8_STAGE(PG8_SB(0, 1), b2 + hstep, voffB); PG8_STAGE(PG8_SA(0, 0), a2, voffA);
;             PG8_WAIT_V(8); PG8_WAIT_L(0); PG8_BAR; PG8_MMA(1, 0, At, B0); PG8_MMA(1, 1, At, B1); PG8_BAR; PG8_SCHED;
.LBB0_144:
	s_add_u32 s20, s8, 0xfffc0080
	s_addc_u32 s21, s9, -1
	s_add_i32 s80, 0, 0x10000
	s_cmp_eq_u32 s73, 12
	s_cselect_b32 s39, s17, s21
	s_cselect_b32 s38, s40, s20
	v_add_u32_e32 v149, s80, v147
	s_cselect_b32 s35, s13, s72
	s_cselect_b32 s34, s41, s46
	s_add_i32 s20, 0, 0x14000
	ds_read_b128 v[142:145], v149
	ds_read_b128 v[150:153], v149 offset:1024
	ds_read_b128 v[154:157], v149 offset:2048
	ds_read_b128 v[158:161], v149 offset:3072
	v_add_u32_e32 v149, s20, v147
	ds_read_b128 v[162:165], v149
	ds_read_b128 v[166:169], v149 offset:1024
	ds_read_b128 v[170:173], v149 offset:2048
	ds_read_b128 v[174:177], v149 offset:3072
	s_add_i32 m0, s28, 0xc000
	ds_read_b128 v[178:181], v148
	ds_read_b128 v[182:185], v148 offset:1024
	ds_read_b128 v[186:189], v148 offset:2048
	ds_read_b128 v[190:193], v148 offset:3072
	ds_read_b128 v[194:197], v148 offset:4096
	ds_read_b128 v[206:209], v148 offset:5120
	ds_read_b128 v[210:213], v148 offset:6144
	ds_read_b128 v[214:217], v148 offset:7168
	global_load_lds_dwordx4 v138, s[8:9]
	s_add_i32 m0, s28, 0xe000
	s_nop 0
	global_load_lds_dwordx4 v140, s[8:9]
	s_waitcnt vmcnt(8) lgkmcnt(0)
	s_barrier
	s_setprio 1
	v_mfma_f32_16x16x32_bf16 v[126:129], v[142:145], v[178:181], v[126:129]
	v_mfma_f32_16x16x32_bf16 v[122:125], v[154:157], v[178:181], v[122:125]
	v_mfma_f32_16x16x32_bf16 v[110:113], v[142:145], v[186:189], v[110:113]
	v_mfma_f32_16x16x32_bf16 v[106:109], v[154:157], v[186:189], v[106:109]
	v_mfma_f32_16x16x32_bf16 v[94:97], v[142:145], v[194:197], v[94:97]
	v_mfma_f32_16x16x32_bf16 v[90:93], v[154:157], v[194:197], v[90:93]
	v_mfma_f32_16x16x32_bf16 v[78:81], v[142:145], v[210:213], v[78:81]
	v_mfma_f32_16x16x32_bf16 v[74:77], v[154:157], v[210:213], v[74:77]
	v_mfma_f32_16x16x32_bf16 v[126:129], v[150:153], v[182:185], v[126:129]
	v_mfma_f32_16x16x32_bf16 v[122:125], v[158:161], v[182:185], v[122:125]
	v_mfma_f32_16x16x32_bf16 v[110:113], v[150:153], v[190:193], v[110:113]
	v_mfma_f32_16x16x32_bf16 v[106:109], v[158:161], v[190:193], v[106:109]
	v_mfma_f32_16x16x32_bf16 v[94:97], v[150:153], v[206:209], v[94:97]
	v_mfma_f32_16x16x32_bf16 v[90:93], v[158:161], v[206:209], v[90:93]
	v_mfma_f32_16x16x32_bf16 v[78:81], v[150:153], v[214:217], v[78:81]
	v_mfma_f32_16x16x32_bf16 v[74:77], v[158:161], v[214:217], v[74:77]
	v_mfma_f32_16x16x32_bf16 v[118:121], v[162:165], v[178:181], v[118:121]
	v_mfma_f32_16x16x32_bf16 v[114:117], v[170:173], v[178:181], v[114:117]
	v_mfma_f32_16x16x32_bf16 v[102:105], v[162:165], v[186:189], v[102:105]
	v_mfma_f32_16x16x32_bf16 v[98:101], v[170:173], v[186:189], v[98:101]
	v_mfma_f32_16x16x32_bf16 v[86:89], v[162:165], v[194:197], v[86:89]
	v_mfma_f32_16x16x32_bf16 v[82:85], v[170:173], v[194:197], v[82:85]
	v_mfma_f32_16x16x32_bf16 v[70:73], v[162:165], v[210:213], v[70:73]
	v_mfma_f32_16x16x32_bf16 v[66:69], v[170:173], v[210:213], v[66:69]
	v_mfma_f32_16x16x32_bf16 v[118:121], v[166:169], v[182:185], v[118:121]
	v_mfma_f32_16x16x32_bf16 v[114:117], v[174:177], v[182:185], v[114:117]
	v_mfma_f32_16x16x32_bf16 v[102:105], v[166:169], v[190:193], v[102:105]
	v_mfma_f32_16x16x32_bf16 v[98:101], v[174:177], v[190:193], v[98:101]
	v_mfma_f32_16x16x32_bf16 v[86:89], v[166:169], v[206:209], v[86:89]
	v_mfma_f32_16x16x32_bf16 v[82:85], v[174:177], v[206:209], v[82:85]
	v_mfma_f32_16x16x32_bf16 v[70:73], v[166:169], v[214:217], v[70:73]
	v_mfma_f32_16x16x32_bf16 v[66:69], v[174:177], v[214:217], v[66:69]
	s_setprio 0
	s_barrier
	s_add_i32 s21, s80, s47
	s_mov_b32 m0, s21
	ds_read_b128 v[178:181], v148 offset:16384
	ds_read_b128 v[182:185], v148 offset:17408
	ds_read_b128 v[186:189], v148 offset:18432
	ds_read_b128 v[190:193], v148 offset:19456
	ds_read_b128 v[194:197], v148 offset:20480
	ds_read_b128 v[206:209], v148 offset:21504
	ds_read_b128 v[210:213], v148 offset:22528
	ds_read_b128 v[214:217], v148 offset:23552
	global_load_lds_dwordx4 v0, s[34:35]
	s_add_i32 m0, s21, 0x2000
	s_add_u32 s82, s34, 0x40000
	s_addc_u32 s83, s35, 0
	s_add_i32 s20, s20, s47
	global_load_lds_dwordx4 v130, s[34:35]
	s_mov_b32 m0, s20
	s_nop 0
	global_load_lds_dwordx4 v0, s[82:83]
	s_add_i32 m0, s20, 0x2000
	s_nop 0
	global_load_lds_dwordx4 v130, s[82:83]
	s_mov_b32 m0, s28
	s_nop 0
	global_load_lds_dwordx4 v134, s[38:39]
	s_mov_b32 m0, s29
	s_nop 0
	global_load_lds_dwordx4 v132, s[38:39]
	s_waitcnt vmcnt(8) lgkmcnt(0)
	s_barrier
	s_setprio 1
	v_mfma_f32_16x16x32_bf16 v[62:65], v[142:145], v[178:181], v[62:65]
	v_mfma_f32_16x16x32_bf16 v[58:61], v[154:157], v[178:181], v[58:61]
	v_mfma_f32_16x16x32_bf16 v[46:49], v[142:145], v[186:189], v[46:49]
	v_mfma_f32_16x16x32_bf16 v[42:45], v[154:157], v[186:189], v[42:45]
	v_mfma_f32_16x16x32_bf16 v[30:33], v[142:145], v[194:197], v[30:33]
	v_mfma_f32_16x16x32_bf16 v[26:29], v[154:157], v[194:197], v[26:29]
	v_mfma_f32_16x16x32_bf16 v[14:17], v[142:145], v[210:213], v[14:17]
	v_mfma_f32_16x16x32_bf16 v[10:13], v[154:157], v[210:213], v[10:13]
	v_mfma_f32_16x16x32_bf16 v[62:65], v[150:153], v[182:185], v[62:65]
	v_mfma_f32_16x16x32_bf16 v[58:61], v[158:161], v[182:185], v[58:61]
	v_mfma_f32_16x16x32_bf16 v[46:49], v[150:153], v[190:193], v[46:49]
	v_mfma_f32_16x16x32_bf16 v[42:45], v[158:161], v[190:193], v[42:45]
	v_mfma_f32_16x16x32_bf16 v[30:33], v[150:153], v[206:209], v[30:33]
	v_mfma_f32_16x16x32_bf16 v[26:29], v[158:161], v[206:209], v[26:29]
	v_mfma_f32_16x16x32_bf16 v[14:17], v[150:153], v[214:217], v[14:17]
	v_mfma_f32_16x16x32_bf16 v[10:13], v[158:161], v[214:217], v[10:13]
	v_mfma_f32_16x16x32_bf16 v[54:57], v[162:165], v[178:181], v[54:57]
	v_mfma_f32_16x16x32_bf16 v[50:53], v[170:173], v[178:181], v[50:53]
	v_mfma_f32_16x16x32_bf16 v[38:41], v[162:165], v[186:189], v[38:41]
	v_mfma_f32_16x16x32_bf16 v[34:37], v[170:173], v[186:189], v[34:37]
	v_mfma_f32_16x16x32_bf16 v[22:25], v[162:165], v[194:197], v[22:25]
	v_mfma_f32_16x16x32_bf16 v[18:21], v[170:173], v[194:197], v[18:21]
	v_mfma_f32_16x16x32_bf16 v[6:9], v[162:165], v[210:213], v[6:9]
	v_mfma_f32_16x16x32_bf16 v[2:5], v[170:173], v[210:213], v[2:5]
	v_mfma_f32_16x16x32_bf16 v[54:57], v[166:169], v[182:185], v[54:57]
	v_mfma_f32_16x16x32_bf16 v[50:53], v[174:177], v[182:185], v[50:53]
	v_mfma_f32_16x16x32_bf16 v[38:41], v[166:169], v[190:193], v[38:41]
	v_mfma_f32_16x16x32_bf16 v[34:37], v[174:177], v[190:193], v[34:37]
	v_mfma_f32_16x16x32_bf16 v[22:25], v[166:169], v[206:209], v[22:25]
	v_mfma_f32_16x16x32_bf16 v[18:21], v[174:177], v[206:209], v[18:21]
	v_mfma_f32_16x16x32_bf16 v[6:9], v[166:169], v[214:217], v[6:9]
	v_mfma_f32_16x16x32_bf16 v[2:5], v[174:177], v[214:217], v[2:5]
	s_setprio 0
	s_barrier
; #define PG8_STAGE(bufoff, gbase, voff) do { _Pragma("unroll") for (int _i = 0; _i < 2; ++_i) \
;         __builtin_amdgcn_global_load_lds((const unsigned*)((const char*)(gbase) + (voff)[_i]), (PG8_LAS unsigned*)(lds + (bufoff) + ldsw + _i * 8192), 16, 0, 0); } while (0)
; #define PG8_LDA(dst, b, h) do { _Pragma("unroll") for (int m = 0; m < 4; ++m) _Pragma("unroll") for (int k = 0; k < 2; ++k) dst[m][k] = *(const PG8_LAS bf16x8*)(lds + PG8_SA(b, h) + aoff + m * 2048 + k * 1024); } while (0)
; #define PG8_LDB(dst, b, h) do { _Pragma("unroll") for (int n = 0; n < 2; ++n) _Pragma("unroll") for (int k = 0; k < 2; ++k) dst[n][k] = *(const PG8_LAS bf16x8*)(lds + PG8_SB(b, h) + boff + n * 2048 + k * 1024); } while (0)
; #define PG8_MMA(ai, bj, At, Bt) do { __builtin_amdgcn_s_setprio(1); _Pragma("unroll") for (int m = 0; m < 4; ++m) _Pragma("unroll") for (int n = 0; n < 2; ++n) _Pragma("unroll") for (int k = 0; k < 2; ++k) \
;         acc[ai][bj][m][n] = __builtin_amdgcn_mfma_f32_16x16x32_bf16(Bt[n][k], At[m][k], acc[ai][bj][m][n], 0, 0, 0); __builtin_amdgcn_s_setprio(0); } while (0)
; #define PG8_WAIT_V(n) asm volatile("s_waitcnt vmcnt(" #n ")" ::: "memory")
; #define PG8_WAIT_L(n) asm volatile("s_waitcnt lgkmcnt(" #n ")" ::: "memory")
; #define PG8_BAR __builtin_amdgcn_s_barrier()
; #define PG8_SCHED __builtin_amdgcn_sched_barrier(0)
; template <class Epi, class Sched, bool ALIGN_EPI = false, bool SP2 = false>
; __device__ __forceinline__ void gemm_phase(PG8_LAS unsigned char* lds, const Gemm g, const Sched& S, const Epi& E) {
;     ...
;             PG8_LDB(B0, 1, 0); PG8_LDB(B1, 1, 1); PG8_SCHED; PG8_LDA(At, 1, 0); PG8_STAGE(PG8_SA(0, 1), a2 + hstep, voffA);
;             PG8_WAIT_V(8); PG8_WAIT_L(0); PG8_BAR; PG8_MMA(0, 0, At, B0); PG8_MMA(0, 1, At, B1); PG8_BAR; PG8_SCHED;
;             PG8_LDA(At, 1, 1); PG8_STAGE(PG8_SB(1, 0), b3, voffB); PG8_STAGE(PG8_SB(1, 1), b3 + hstep, voffB); PG8_STAGE(PG8_SA(1, 0), a3, voffA);
;             PG8_WAIT_V(8); PG8_WAIT_L(0); PG8_BAR; PG8_MMA(1, 0, At, B0); PG8_MMA(1, 1, At, B1); PG8_BAR; PG8_SCHED;
	s_add_i32 s20, 0, 0x18000
	v_add_u32_e32 v149, s20, v147
	s_add_i32 s21, 0, 0x1c000
	ds_read_b128 v[142:145], v149
	ds_read_b128 v[150:153], v149 offset:1024
	ds_read_b128 v[154:157], v149 offset:2048
	ds_read_b128 v[158:161], v149 offset:3072
	v_add_u32_e32 v149, s21, v147
	ds_read_b128 v[162:165], v149
	ds_read_b128 v[166:169], v149 offset:1024
	ds_read_b128 v[170:173], v149 offset:2048
	ds_read_b128 v[174:177], v149 offset:3072
	s_add_u32 vcc_lo, s38, 0x40000
	s_addc_u32 vcc_hi, s39, 0
	s_mov_b32 m0, s52
	ds_read_b128 v[178:181], v148 offset:32768
	ds_read_b128 v[182:185], v148 offset:33792
	ds_read_b128 v[186:189], v148 offset:34816
	ds_read_b128 v[190:193], v148 offset:35840
	ds_read_b128 v[194:197], v148 offset:36864
	ds_read_b128 v[206:209], v148 offset:37888
	ds_read_b128 v[210:213], v148 offset:38912
	ds_read_b128 v[214:217], v148 offset:39936
	global_load_lds_dwordx4 v134, vcc
	s_mov_b32 m0, s53
	s_nop 0
	global_load_lds_dwordx4 v132, vcc
	s_waitcnt vmcnt(8) lgkmcnt(0)
	s_barrier
	s_setprio 1
	v_mfma_f32_16x16x32_bf16 v[126:129], v[142:145], v[178:181], v[126:129]
	v_mfma_f32_16x16x32_bf16 v[122:125], v[154:157], v[178:181], v[122:125]
	v_mfma_f32_16x16x32_bf16 v[110:113], v[142:145], v[186:189], v[110:113]
	v_mfma_f32_16x16x32_bf16 v[106:109], v[154:157], v[186:189], v[106:109]
	v_mfma_f32_16x16x32_bf16 v[94:97], v[142:145], v[194:197], v[94:97]
	v_mfma_f32_16x16x32_bf16 v[90:93], v[154:157], v[194:197], v[90:93]
	v_mfma_f32_16x16x32_bf16 v[78:81], v[142:145], v[210:213], v[78:81]
	v_mfma_f32_16x16x32_bf16 v[74:77], v[154:157], v[210:213], v[74:77]
	v_mfma_f32_16x16x32_bf16 v[126:129], v[150:153], v[182:185], v[126:129]
	v_mfma_f32_16x16x32_bf16 v[122:125], v[158:161], v[182:185], v[122:125]
	v_mfma_f32_16x16x32_bf16 v[110:113], v[150:153], v[190:193], v[110:113]
	v_mfma_f32_16x16x32_bf16 v[106:109], v[158:161], v[190:193], v[106:109]
	v_mfma_f32_16x16x32_bf16 v[94:97], v[150:153], v[206:209], v[94:97]
	v_mfma_f32_16x16x32_bf16 v[90:93], v[158:161], v[206:209], v[90:93]
	v_mfma_f32_16x16x32_bf16 v[78:81], v[150:153], v[214:217], v[78:81]
	v_mfma_f32_16x16x32_bf16 v[74:77], v[158:161], v[214:217], v[74:77]
	v_mfma_f32_16x16x32_bf16 v[118:121], v[162:165], v[178:181], v[118:121]
	v_mfma_f32_16x16x32_bf16 v[114:117], v[170:173], v[178:181], v[114:117]
	v_mfma_f32_16x16x32_bf16 v[102:105], v[162:165], v[186:189], v[102:105]
	v_mfma_f32_16x16x32_bf16 v[98:101], v[170:173], v[186:189], v[98:101]
	v_mfma_f32_16x16x32_bf16 v[86:89], v[162:165], v[194:197], v[86:89]
	v_mfma_f32_16x16x32_bf16 v[82:85], v[170:173], v[194:197], v[82:85]
	v_mfma_f32_16x16x32_bf16 v[70:73], v[162:165], v[210:213], v[70:73]
	v_mfma_f32_16x16x32_bf16 v[66:69], v[170:173], v[210:213], v[66:69]
	v_mfma_f32_16x16x32_bf16 v[118:121], v[166:169], v[182:185], v[118:121]
	v_mfma_f32_16x16x32_bf16 v[114:117], v[174:177], v[182:185], v[114:117]
	v_mfma_f32_16x16x32_bf16 v[102:105], v[166:169], v[190:193], v[102:105]
	v_mfma_f32_16x16x32_bf16 v[98:101], v[174:177], v[190:193], v[98:101]
	v_mfma_f32_16x16x32_bf16 v[86:89], v[166:169], v[206:209], v[86:89]
	v_mfma_f32_16x16x32_bf16 v[82:85], v[174:177], v[206:209], v[82:85]
	v_mfma_f32_16x16x32_bf16 v[70:73], v[166:169], v[214:217], v[70:73]
	v_mfma_f32_16x16x32_bf16 v[66:69], v[174:177], v[214:217], v[66:69]
	s_setprio 0
	s_barrier
	s_add_i32 s20, s20, s47
	s_add_i32 m0, s20, 0xffffff80
	ds_read_b128 v[178:181], v148 offset:49152
	ds_read_b128 v[182:185], v148 offset:50176
	ds_read_b128 v[186:189], v148 offset:51200
	ds_read_b128 v[190:193], v148 offset:52224
	ds_read_b128 v[194:197], v148 offset:53248
	ds_read_b128 v[206:209], v148 offset:54272
	ds_read_b128 v[210:213], v148 offset:55296
	ds_read_b128 v[214:217], v148 offset:56320
	global_load_lds_dwordx4 v0, s[34:35] offset:128
	s_add_i32 m0, s20, 0x1f80
	s_add_i32 s20, s21, s47
	global_load_lds_dwordx4 v130, s[34:35] offset:128
	s_add_u32 s34, s34, 0x40080
	s_addc_u32 s35, s35, 0
	s_mov_b32 m0, s20
	s_nop 0
	global_load_lds_dwordx4 v0, s[34:35]
	s_add_i32 m0, s20, 0x2000
	s_nop 0
	global_load_lds_dwordx4 v130, s[34:35]
	s_add_i32 m0, s55, 0xffffff80
	s_nop 0
	global_load_lds_dwordx4 v134, s[38:39] offset:128
	s_add_i32 m0, s57, 0xffffff80
	s_nop 0
	global_load_lds_dwordx4 v132, s[38:39] offset:128
	s_waitcnt vmcnt(8) lgkmcnt(0)
	s_barrier
	s_setprio 1
	v_mfma_f32_16x16x32_bf16 v[62:65], v[142:145], v[178:181], v[62:65]
	v_mfma_f32_16x16x32_bf16 v[58:61], v[154:157], v[178:181], v[58:61]
	v_mfma_f32_16x16x32_bf16 v[46:49], v[142:145], v[186:189], v[46:49]
	v_mfma_f32_16x16x32_bf16 v[42:45], v[154:157], v[186:189], v[42:45]
	v_mfma_f32_16x16x32_bf16 v[30:33], v[142:145], v[194:197], v[30:33]
	v_mfma_f32_16x16x32_bf16 v[26:29], v[154:157], v[194:197], v[26:29]
	v_mfma_f32_16x16x32_bf16 v[14:17], v[142:145], v[210:213], v[14:17]
	v_mfma_f32_16x16x32_bf16 v[10:13], v[154:157], v[210:213], v[10:13]
	v_mfma_f32_16x16x32_bf16 v[62:65], v[150:153], v[182:185], v[62:65]
	v_mfma_f32_16x16x32_bf16 v[58:61], v[158:161], v[182:185], v[58:61]
	v_mfma_f32_16x16x32_bf16 v[46:49], v[150:153], v[190:193], v[46:49]
	v_mfma_f32_16x16x32_bf16 v[42:45], v[158:161], v[190:193], v[42:45]
	v_mfma_f32_16x16x32_bf16 v[30:33], v[150:153], v[206:209], v[30:33]
	v_mfma_f32_16x16x32_bf16 v[26:29], v[158:161], v[206:209], v[26:29]
	v_mfma_f32_16x16x32_bf16 v[14:17], v[150:153], v[214:217], v[14:17]
	v_mfma_f32_16x16x32_bf16 v[10:13], v[158:161], v[214:217], v[10:13]
	v_mfma_f32_16x16x32_bf16 v[54:57], v[162:165], v[178:181], v[54:57]
	v_mfma_f32_16x16x32_bf16 v[50:53], v[170:173], v[178:181], v[50:53]
	v_mfma_f32_16x16x32_bf16 v[38:41], v[162:165], v[186:189], v[38:41]
	v_mfma_f32_16x16x32_bf16 v[34:37], v[170:173], v[186:189], v[34:37]
	v_mfma_f32_16x16x32_bf16 v[22:25], v[162:165], v[194:197], v[22:25]
	v_mfma_f32_16x16x32_bf16 v[18:21], v[170:173], v[194:197], v[18:21]
	v_mfma_f32_16x16x32_bf16 v[6:9], v[162:165], v[210:213], v[6:9]
	v_mfma_f32_16x16x32_bf16 v[2:5], v[170:173], v[210:213], v[2:5]
	v_mfma_f32_16x16x32_bf16 v[54:57], v[166:169], v[182:185], v[54:57]
	v_mfma_f32_16x16x32_bf16 v[50:53], v[174:177], v[182:185], v[50:53]
	v_mfma_f32_16x16x32_bf16 v[38:41], v[166:169], v[190:193], v[38:41]
	v_mfma_f32_16x16x32_bf16 v[34:37], v[174:177], v[190:193], v[34:37]
	v_mfma_f32_16x16x32_bf16 v[22:25], v[166:169], v[206:209], v[22:25]
	v_mfma_f32_16x16x32_bf16 v[18:21], v[174:177], v[206:209], v[18:21]
	v_mfma_f32_16x16x32_bf16 v[6:9], v[166:169], v[214:217], v[6:9]
	v_mfma_f32_16x16x32_bf16 v[2:5], v[174:177], v[214:217], v[2:5]
	s_setprio 0
	s_barrier
	s_add_i32 s73, s73, 2
	s_add_u32 s8, s8, 0x100
	s_addc_u32 s9, s9, 0
	s_add_u32 s46, s46, 0x100
	s_addc_u32 s72, s72, 0
	s_cmp_gt_u32 s73, 13
	s_cbranch_scc0 .LBB0_144
	s_and_b64 vcc, exec, s[6:7]
	s_cbranch_vccz .LBB0_147
	s_barrier

; #define PG8_STAGE(bufoff, gbase, voff) do { _Pragma("unroll") for (int _i = 0; _i < 2; ++_i) \
;         __builtin_amdgcn_global_load_lds((const unsigned*)((const char*)(gbase) + (voff)[_i]), (PG8_LAS unsigned*)(lds + (bufoff) + ldsw + _i * 8192), 16, 0, 0); } while (0)
; #define PG8_LDA(dst, b, h) do { _Pragma("unroll") for (int m = 0; m < 4; ++m) _Pragma("unroll") for (int k = 0; k < 2; ++k) dst[m][k] = *(const PG8_LAS bf16x8*)(lds + PG8_SA(b, h) + aoff + m * 2048 + k * 1024); } while (0)
; #define PG8_LDB(dst, b, h) do { _Pragma("unroll") for (int n = 0; n < 2; ++n) _Pragma("unroll") for (int k = 0; k < 2; ++k) dst[n][k] = *(const PG8_LAS bf16x8*)(lds + PG8_SB(b, h) + boff + n * 2048 + k * 1024); } while (0)
; #define PG8_MMA(ai, bj, At, Bt) do { __builtin_amdgcn_s_setprio(1); _Pragma("unroll") for (int m = 0; m < 4; ++m) _Pragma("unroll") for (int n = 0; n < 2; ++n) _Pragma("unroll") for (int k = 0; k < 2; ++k) \
;         acc[ai][bj][m][n] = __builtin_amdgcn_mfma_f32_16x16x32_bf16(Bt[n][k], At[m][k], acc[ai][bj][m][n], 0, 0, 0); __builtin_amdgcn_s_setprio(0); } while (0)
; #define PG8_WAIT_V(n) asm volatile("s_waitcnt vmcnt(" #n ")" ::: "memory")
; #define PG8_WAIT_L(n) asm volatile("s_waitcnt lgkmcnt(" #n ")" ::: "memory")
; template <class Epi, class Sched, bool ALIGN_EPI = false, bool SP2 = false>
; __device__ __forceinline__ void gemm_phase(PG8_LAS unsigned char* lds, const Gemm g, const Sched& S, const Epi& E) {
;     ...
;             const bool last = (t == nt - 2);
;             const char* a1 = cA + (size_t)(t + 1) * kstep;
;             const char* a2 = last ? nA : cA + (size_t)(t + 2) * kstep; const char* b2 = last ? nB : cB + (size_t)(t + 2) * kstep;
;             const char* a3 = a2 + kstep; const char* b3 = b2 + kstep;
;             if (last && has_next) S.a_ready(nxt);
;             if constexpr (SP2) {
;             PG8_LDB(B0, 0, 0); PG8_LDB(B1, 0, 1); PG8_SCHED; PG8_LDA(At, 0, 0); PG8_STAGE(PG8_SA(1, 1), a1 + hstep, voffA);
;             PG8_WAIT_V(8); PG8_WAIT_L(0); PG8_BAR; PG8_MMA(0, 0, At, B0); PG8_MMA(0, 1, At, B1); PG8_BAR; PG8_SCHED;
;             PG8_LDA(At, 0, 1); PG8_STAGE(PG8_SB(0, 0), b2, voffB); PG8_STAGE(PG8_SB(0, 1), b2 + hstep, voffB); PG8_STAGE(PG8_SA(0, 0), a2, voffA);
;             PG8_WAIT_V(8); PG8_WAIT_L(0); PG8_BAR; PG8_MMA(1, 0, At, B0); PG8_MMA(1, 1, At, B1); PG8_BAR; PG8_SCHED;
.LBB0_351:
	s_add_u32 s20, s8, 0xfffc0080
	s_addc_u32 s21, s9, -1
	s_add_i32 s80, 0, 0x10000
	s_cmp_eq_u32 s73, 12
	s_cselect_b32 s35, s17, s21
	s_cselect_b32 s34, s40, s20
	s_cselect_b32 s31, s13, s72
	s_cselect_b32 s30, s41, s58
	s_add_i32 s81, 0, 0x14000
	v_add_u32_e32 v148, s80, v153
	v_add_u32_e32 v168, s81, v153
	ds_read_b128 v[130:133], v148
	ds_read_b128 v[134:137], v148 offset:1024
	ds_read_b128 v[138:141], v148 offset:2048
	ds_read_b128 v[148:151], v148 offset:3072
	ds_read_b128 v[156:159], v168
	ds_read_b128 v[160:163], v168 offset:1024
	ds_read_b128 v[164:167], v168 offset:2048
	ds_read_b128 v[168:171], v168 offset:3072
	v_lshl_add_u64 v[196:197], s[8:9], 0, v[144:145]
	s_add_i32 m0, s43, 0xc000
	ds_read_b128 v[172:175], v155
	ds_read_b128 v[176:179], v155 offset:1024
	ds_read_b128 v[180:183], v155 offset:2048
	ds_read_b128 v[184:187], v155 offset:3072
	ds_read_b128 v[188:191], v155 offset:4096
	ds_read_b128 v[192:195], v155 offset:5120
	ds_read_b128 v[206:209], v155 offset:6144
	ds_read_b128 v[210:213], v155 offset:7168
	global_load_lds_dwordx4 v[196:197], off
	s_add_i32 m0, s43, 0xe000
	v_lshl_add_u64 v[196:197], s[8:9], 0, v[146:147]
	global_load_lds_dwordx4 v[196:197], off
	s_waitcnt vmcnt(8) lgkmcnt(0)
	s_barrier
	s_setprio 1
	v_mfma_f32_16x16x32_bf16 v[126:129], v[130:133], v[172:175], v[126:129]
	v_mfma_f32_16x16x32_bf16 v[122:125], v[138:141], v[172:175], v[122:125]
	v_mfma_f32_16x16x32_bf16 v[118:121], v[130:133], v[180:183], v[118:121]
	v_mfma_f32_16x16x32_bf16 v[106:109], v[138:141], v[180:183], v[106:109]
	v_mfma_f32_16x16x32_bf16 v[102:105], v[130:133], v[188:191], v[102:105]
	v_mfma_f32_16x16x32_bf16 v[90:93], v[138:141], v[188:191], v[90:93]
	v_mfma_f32_16x16x32_bf16 v[86:89], v[130:133], v[206:209], v[86:89]
	v_mfma_f32_16x16x32_bf16 v[74:77], v[138:141], v[206:209], v[74:77]
	v_mfma_f32_16x16x32_bf16 v[126:129], v[134:137], v[176:179], v[126:129]
	v_mfma_f32_16x16x32_bf16 v[122:125], v[148:151], v[176:179], v[122:125]
	v_mfma_f32_16x16x32_bf16 v[118:121], v[134:137], v[184:187], v[118:121]
	v_mfma_f32_16x16x32_bf16 v[106:109], v[148:151], v[184:187], v[106:109]
	v_mfma_f32_16x16x32_bf16 v[102:105], v[134:137], v[192:195], v[102:105]
	v_mfma_f32_16x16x32_bf16 v[90:93], v[148:151], v[192:195], v[90:93]
	v_mfma_f32_16x16x32_bf16 v[86:89], v[134:137], v[210:213], v[86:89]
	v_mfma_f32_16x16x32_bf16 v[74:77], v[148:151], v[210:213], v[74:77]
	v_mfma_f32_16x16x32_bf16 v[114:117], v[156:159], v[172:175], v[114:117]
	v_mfma_f32_16x16x32_bf16 v[110:113], v[164:167], v[172:175], v[110:113]
	v_mfma_f32_16x16x32_bf16 v[98:101], v[156:159], v[180:183], v[98:101]
	v_mfma_f32_16x16x32_bf16 v[94:97], v[164:167], v[180:183], v[94:97]
	v_mfma_f32_16x16x32_bf16 v[82:85], v[156:159], v[188:191], v[82:85]
	v_mfma_f32_16x16x32_bf16 v[78:81], v[164:167], v[188:191], v[78:81]
	v_mfma_f32_16x16x32_bf16 v[70:73], v[156:159], v[206:209], v[70:73]
	v_mfma_f32_16x16x32_bf16 v[66:69], v[164:167], v[206:209], v[66:69]
	v_mfma_f32_16x16x32_bf16 v[114:117], v[160:163], v[176:179], v[114:117]
	v_mfma_f32_16x16x32_bf16 v[110:113], v[168:171], v[176:179], v[110:113]
	v_mfma_f32_16x16x32_bf16 v[98:101], v[160:163], v[184:187], v[98:101]
	v_mfma_f32_16x16x32_bf16 v[94:97], v[168:171], v[184:187], v[94:97]
	v_mfma_f32_16x16x32_bf16 v[82:85], v[160:163], v[192:195], v[82:85]
	v_mfma_f32_16x16x32_bf16 v[78:81], v[168:171], v[192:195], v[78:81]
	v_mfma_f32_16x16x32_bf16 v[70:73], v[160:163], v[210:213], v[70:73]
	v_mfma_f32_16x16x32_bf16 v[66:69], v[168:171], v[210:213], v[66:69]
	s_setprio 0
	s_barrier
	s_add_i32 s20, s80, s42
	v_lshl_add_u64 v[196:197], s[30:31], 0, v[0:1]
	s_mov_b32 m0, s20
	ds_read_b128 v[172:175], v155 offset:16384
	ds_read_b128 v[176:179], v155 offset:17408
	ds_read_b128 v[180:183], v155 offset:18432
	ds_read_b128 v[184:187], v155 offset:19456
	ds_read_b128 v[188:191], v155 offset:20480
	ds_read_b128 v[192:195], v155 offset:21504
	ds_read_b128 v[206:209], v155 offset:22528
	ds_read_b128 v[210:213], v155 offset:23552
	global_load_lds_dwordx4 v[196:197], off
	s_add_i32 m0, s20, 0x2000
	s_add_u32 s20, s30, 0x40000
	v_lshl_add_u64 v[214:215], s[30:31], 0, v[142:143]
	s_addc_u32 s21, s31, 0
	s_add_i32 s80, s81, s42
	global_load_lds_dwordx4 v[214:215], off
	v_lshl_add_u64 v[216:217], s[20:21], 0, v[0:1]
	s_mov_b32 m0, s80
	v_lshl_add_u64 v[218:219], s[34:35], 0, v[142:143]
	global_load_lds_dwordx4 v[216:217], off
	s_add_i32 m0, s80, 0x2000
	v_lshl_add_u64 v[216:217], s[20:21], 0, v[142:143]
	global_load_lds_dwordx4 v[216:217], off
	s_mov_b32 m0, s43
	v_lshl_add_u64 v[216:217], s[34:35], 0, v[0:1]
	global_load_lds_dwordx4 v[216:217], off
	s_mov_b32 m0, s46
	s_nop 0
	global_load_lds_dwordx4 v[218:219], off
	s_waitcnt vmcnt(8) lgkmcnt(0)
	s_barrier
; #define PG8_STAGE(bufoff, gbase, voff) do { _Pragma("unroll") for (int _i = 0; _i < 2; ++_i) \
;         __builtin_amdgcn_global_load_lds((const unsigned*)((const char*)(gbase) + (voff)[_i]), (PG8_LAS unsigned*)(lds + (bufoff) + ldsw + _i * 8192), 16, 0, 0); } while (0)
; #define PG8_LDA(dst, b, h) do { _Pragma("unroll") for (int m = 0; m < 4; ++m) _Pragma("unroll") for (int k = 0; k < 2; ++k) dst[m][k] = *(const PG8_LAS bf16x8*)(lds + PG8_SA(b, h) + aoff + m * 2048 + k * 1024); } while (0)
; #define PG8_LDB(dst, b, h) do { _Pragma("unroll") for (int n = 0; n < 2; ++n) _Pragma("unroll") for (int k = 0; k < 2; ++k) dst[n][k] = *(const PG8_LAS bf16x8*)(lds + PG8_SB(b, h) + boff + n * 2048 + k * 1024); } while (0)
; #define PG8_MMA(ai, bj, At, Bt) do { __builtin_amdgcn_s_setprio(1); _Pragma("unroll") for (int m = 0; m < 4; ++m) _Pragma("unroll") for (int n = 0; n < 2; ++n) _Pragma("unroll") for (int k = 0; k < 2; ++k) \
;         acc[ai][bj][m][n] = __builtin_amdgcn_mfma_f32_16x16x32_bf16(Bt[n][k], At[m][k], acc[ai][bj][m][n], 0, 0, 0); __builtin_amdgcn_s_setprio(0); } while (0)
; #define PG8_WAIT_V(n) asm volatile("s_waitcnt vmcnt(" #n ")" ::: "memory")
; #define PG8_WAIT_L(n) asm volatile("s_waitcnt lgkmcnt(" #n ")" ::: "memory")
; #define PG8_BAR __builtin_amdgcn_s_barrier()
; #define PG8_SCHED __builtin_amdgcn_sched_barrier(0)
; template <class Epi, class Sched, bool ALIGN_EPI = false, bool SP2 = false>
; __device__ __forceinline__ void gemm_phase(PG8_LAS unsigned char* lds, const Gemm g, const Sched& S, const Epi& E) {
;     ...
;             PG8_WAIT_V(8); PG8_WAIT_L(0); PG8_BAR; PG8_MMA(1, 0, At, B0); PG8_MMA(1, 1, At, B1); PG8_BAR; PG8_SCHED;
;             PG8_LDB(B0, 1, 0); PG8_LDB(B1, 1, 1); PG8_SCHED; PG8_LDA(At, 1, 0); PG8_STAGE(PG8_SA(0, 1), a2 + hstep, voffA);
;             PG8_WAIT_V(8); PG8_WAIT_L(0); PG8_BAR; PG8_MMA(0, 0, At, B0); PG8_MMA(0, 1, At, B1); PG8_BAR; PG8_SCHED;
	s_setprio 1
	v_mfma_f32_16x16x32_bf16 v[62:65], v[130:133], v[172:175], v[62:65]
	v_mfma_f32_16x16x32_bf16 v[58:61], v[138:141], v[172:175], v[58:61]
	v_mfma_f32_16x16x32_bf16 v[54:57], v[130:133], v[180:183], v[54:57]
	v_mfma_f32_16x16x32_bf16 v[42:45], v[138:141], v[180:183], v[42:45]
	v_mfma_f32_16x16x32_bf16 v[38:41], v[130:133], v[188:191], v[38:41]
	v_mfma_f32_16x16x32_bf16 v[26:29], v[138:141], v[188:191], v[26:29]
	v_mfma_f32_16x16x32_bf16 v[18:21], v[130:133], v[206:209], v[18:21]
	v_mfma_f32_16x16x32_bf16 v[10:13], v[138:141], v[206:209], v[10:13]
	v_mfma_f32_16x16x32_bf16 v[62:65], v[134:137], v[176:179], v[62:65]
	v_mfma_f32_16x16x32_bf16 v[58:61], v[148:151], v[176:179], v[58:61]
	v_mfma_f32_16x16x32_bf16 v[54:57], v[134:137], v[184:187], v[54:57]
	v_mfma_f32_16x16x32_bf16 v[42:45], v[148:151], v[184:187], v[42:45]
	v_mfma_f32_16x16x32_bf16 v[38:41], v[134:137], v[192:195], v[38:41]
	v_mfma_f32_16x16x32_bf16 v[26:29], v[148:151], v[192:195], v[26:29]
	v_mfma_f32_16x16x32_bf16 v[18:21], v[134:137], v[210:213], v[18:21]
	v_mfma_f32_16x16x32_bf16 v[10:13], v[148:151], v[210:213], v[10:13]
	v_mfma_f32_16x16x32_bf16 v[50:53], v[156:159], v[172:175], v[50:53]
	v_mfma_f32_16x16x32_bf16 v[46:49], v[164:167], v[172:175], v[46:49]
	v_mfma_f32_16x16x32_bf16 v[34:37], v[156:159], v[180:183], v[34:37]
	v_mfma_f32_16x16x32_bf16 v[30:33], v[164:167], v[180:183], v[30:33]
	v_mfma_f32_16x16x32_bf16 v[22:25], v[156:159], v[188:191], v[22:25]
	v_mfma_f32_16x16x32_bf16 v[14:17], v[164:167], v[188:191], v[14:17]
	v_mfma_f32_16x16x32_bf16 v[6:9], v[156:159], v[206:209], v[6:9]
	v_mfma_f32_16x16x32_bf16 v[2:5], v[164:167], v[206:209], v[2:5]
	v_mfma_f32_16x16x32_bf16 v[50:53], v[160:163], v[176:179], v[50:53]
	v_mfma_f32_16x16x32_bf16 v[46:49], v[168:171], v[176:179], v[46:49]
	v_mfma_f32_16x16x32_bf16 v[34:37], v[160:163], v[184:187], v[34:37]
	v_mfma_f32_16x16x32_bf16 v[30:33], v[168:171], v[184:187], v[30:33]
	v_mfma_f32_16x16x32_bf16 v[22:25], v[160:163], v[192:195], v[22:25]
	v_mfma_f32_16x16x32_bf16 v[14:17], v[168:171], v[192:195], v[14:17]
	v_mfma_f32_16x16x32_bf16 v[6:9], v[160:163], v[210:213], v[6:9]
	v_mfma_f32_16x16x32_bf16 v[2:5], v[168:171], v[210:213], v[2:5]
	s_setprio 0
	s_barrier
	s_add_i32 s80, 0, 0x18000
	s_add_i32 s81, 0, 0x1c000
	v_add_u32_e32 v148, s80, v153
	v_add_u32_e32 v168, s81, v153
	ds_read_b128 v[130:133], v148
	ds_read_b128 v[134:137], v148 offset:1024
	ds_read_b128 v[138:141], v148 offset:2048
	ds_read_b128 v[148:151], v148 offset:3072
	ds_read_b128 v[156:159], v168
	ds_read_b128 v[160:163], v168 offset:1024
	ds_read_b128 v[164:167], v168 offset:2048
	ds_read_b128 v[168:171], v168 offset:3072
	s_add_u32 s20, s34, 0x40000
	s_addc_u32 s21, s35, 0
	s_mov_b32 m0, s47
	v_lshl_add_u64 v[220:221], s[20:21], 0, v[0:1]
	ds_read_b128 v[172:175], v155 offset:32768
	ds_read_b128 v[176:179], v155 offset:33792
	ds_read_b128 v[180:183], v155 offset:34816
	ds_read_b128 v[184:187], v155 offset:35840
	ds_read_b128 v[188:191], v155 offset:36864
	ds_read_b128 v[192:195], v155 offset:37888
	ds_read_b128 v[206:209], v155 offset:38912
	ds_read_b128 v[210:213], v155 offset:39936
	global_load_lds_dwordx4 v[220:221], off
	s_mov_b32 m0, s52
	v_lshl_add_u64 v[220:221], s[20:21], 0, v[142:143]
	global_load_lds_dwordx4 v[220:221], off
	s_waitcnt vmcnt(8) lgkmcnt(0)
	s_barrier
	s_setprio 1
	v_mfma_f32_16x16x32_bf16 v[126:129], v[130:133], v[172:175], v[126:129]
	v_mfma_f32_16x16x32_bf16 v[122:125], v[138:141], v[172:175], v[122:125]
	v_mfma_f32_16x16x32_bf16 v[118:121], v[130:133], v[180:183], v[118:121]
	v_mfma_f32_16x16x32_bf16 v[106:109], v[138:141], v[180:183], v[106:109]
	v_mfma_f32_16x16x32_bf16 v[102:105], v[130:133], v[188:191], v[102:105]
	v_mfma_f32_16x16x32_bf16 v[90:93], v[138:141], v[188:191], v[90:93]
	v_mfma_f32_16x16x32_bf16 v[86:89], v[130:133], v[206:209], v[86:89]
	v_mfma_f32_16x16x32_bf16 v[74:77], v[138:141], v[206:209], v[74:77]
	v_mfma_f32_16x16x32_bf16 v[126:129], v[134:137], v[176:179], v[126:129]
	v_mfma_f32_16x16x32_bf16 v[122:125], v[148:151], v[176:179], v[122:125]
	v_mfma_f32_16x16x32_bf16 v[118:121], v[134:137], v[184:187], v[118:121]
	v_mfma_f32_16x16x32_bf16 v[106:109], v[148:151], v[184:187], v[106:109]
	v_mfma_f32_16x16x32_bf16 v[102:105], v[134:137], v[192:195], v[102:105]
	v_mfma_f32_16x16x32_bf16 v[90:93], v[148:151], v[192:195], v[90:93]
	v_mfma_f32_16x16x32_bf16 v[86:89], v[134:137], v[210:213], v[86:89]
	v_mfma_f32_16x16x32_bf16 v[74:77], v[148:151], v[210:213], v[74:77]
	v_mfma_f32_16x16x32_bf16 v[114:117], v[156:159], v[172:175], v[114:117]
	v_mfma_f32_16x16x32_bf16 v[110:113], v[164:167], v[172:175], v[110:113]
	v_mfma_f32_16x16x32_bf16 v[98:101], v[156:159], v[180:183], v[98:101]
	v_mfma_f32_16x16x32_bf16 v[94:97], v[164:167], v[180:183], v[94:97]
	v_mfma_f32_16x16x32_bf16 v[82:85], v[156:159], v[188:191], v[82:85]
	v_mfma_f32_16x16x32_bf16 v[78:81], v[164:167], v[188:191], v[78:81]
	v_mfma_f32_16x16x32_bf16 v[70:73], v[156:159], v[206:209], v[70:73]
	v_mfma_f32_16x16x32_bf16 v[66:69], v[164:167], v[206:209], v[66:69]
	v_mfma_f32_16x16x32_bf16 v[114:117], v[160:163], v[176:179], v[114:117]
	v_mfma_f32_16x16x32_bf16 v[110:113], v[168:171], v[176:179], v[110:113]
	v_mfma_f32_16x16x32_bf16 v[98:101], v[160:163], v[184:187], v[98:101]
	v_mfma_f32_16x16x32_bf16 v[94:97], v[168:171], v[184:187], v[94:97]
	v_mfma_f32_16x16x32_bf16 v[82:85], v[160:163], v[192:195], v[82:85]
	v_mfma_f32_16x16x32_bf16 v[78:81], v[168:171], v[192:195], v[78:81]
	v_mfma_f32_16x16x32_bf16 v[70:73], v[160:163], v[210:213], v[70:73]
	v_mfma_f32_16x16x32_bf16 v[66:69], v[168:171], v[210:213], v[66:69]
	s_setprio 0
	s_barrier
; #define PG8_STAGE(bufoff, gbase, voff) do { _Pragma("unroll") for (int _i = 0; _i < 2; ++_i) \
;         __builtin_amdgcn_global_load_lds((const unsigned*)((const char*)(gbase) + (voff)[_i]), (PG8_LAS unsigned*)(lds + (bufoff) + ldsw + _i * 8192), 16, 0, 0); } while (0)
; #define PG8_LDA(dst, b, h) do { _Pragma("unroll") for (int m = 0; m < 4; ++m) _Pragma("unroll") for (int k = 0; k < 2; ++k) dst[m][k] = *(const PG8_LAS bf16x8*)(lds + PG8_SA(b, h) + aoff + m * 2048 + k * 1024); } while (0)
; #define PG8_MMA(ai, bj, At, Bt) do { __builtin_amdgcn_s_setprio(1); _Pragma("unroll") for (int m = 0; m < 4; ++m) _Pragma("unroll") for (int n = 0; n < 2; ++n) _Pragma("unroll") for (int k = 0; k < 2; ++k) \
;         acc[ai][bj][m][n] = __builtin_amdgcn_mfma_f32_16x16x32_bf16(Bt[n][k], At[m][k], acc[ai][bj][m][n], 0, 0, 0); __builtin_amdgcn_s_setprio(0); } while (0)
; #define PG8_WAIT_V(n) asm volatile("s_waitcnt vmcnt(" #n ")" ::: "memory")
; #define PG8_WAIT_L(n) asm volatile("s_waitcnt lgkmcnt(" #n ")" ::: "memory")
; #define PG8_BAR __builtin_amdgcn_s_barrier()
; #define PG8_SCHED __builtin_amdgcn_sched_barrier(0)
; template <class Epi, class Sched, bool ALIGN_EPI = false, bool SP2 = false>
; __device__ __forceinline__ void gemm_phase(PG8_LAS unsigned char* lds, const Gemm g, const Sched& S, const Epi& E) {
;     ...
;             PG8_LDA(At, 1, 1); PG8_STAGE(PG8_SB(1, 0), b3, voffB); PG8_STAGE(PG8_SB(1, 1), b3 + hstep, voffB); PG8_STAGE(PG8_SA(1, 0), a3, voffA);
;             PG8_WAIT_V(8); PG8_WAIT_L(0); PG8_BAR; PG8_MMA(1, 0, At, B0); PG8_MMA(1, 1, At, B1); PG8_BAR; PG8_SCHED;
	s_add_i32 s20, s80, s42
	v_lshl_add_u64 v[196:197], v[196:197], 0, s[24:25]
	s_mov_b32 m0, s20
	ds_read_b128 v[172:175], v155 offset:49152
	ds_read_b128 v[176:179], v155 offset:50176
	ds_read_b128 v[180:183], v155 offset:51200
	ds_read_b128 v[184:187], v155 offset:52224
	ds_read_b128 v[188:191], v155 offset:53248
	ds_read_b128 v[192:195], v155 offset:54272
	ds_read_b128 v[206:209], v155 offset:55296
	ds_read_b128 v[210:213], v155 offset:56320
	global_load_lds_dwordx4 v[196:197], off
	s_add_i32 m0, s20, 0x2000
	s_add_u32 s20, s30, 0x40080
	v_lshl_add_u64 v[196:197], v[214:215], 0, s[24:25]
	s_addc_u32 s21, s31, 0
	s_add_i32 s30, s81, s42
	global_load_lds_dwordx4 v[196:197], off
	s_mov_b32 m0, s30
	v_lshl_add_u64 v[196:197], s[20:21], 0, v[0:1]
	global_load_lds_dwordx4 v[196:197], off
	s_add_i32 m0, s30, 0x2000
	v_lshl_add_u64 v[196:197], s[20:21], 0, v[142:143]
	global_load_lds_dwordx4 v[196:197], off
	s_mov_b32 m0, s53
	v_lshl_add_u64 v[196:197], v[216:217], 0, s[24:25]
	global_load_lds_dwordx4 v[196:197], off
	s_mov_b32 m0, s55
	v_lshl_add_u64 v[196:197], v[218:219], 0, s[24:25]
	global_load_lds_dwordx4 v[196:197], off
	s_waitcnt vmcnt(8) lgkmcnt(0)
	s_barrier
	s_setprio 1
	v_mfma_f32_16x16x32_bf16 v[62:65], v[130:133], v[172:175], v[62:65]
	v_mfma_f32_16x16x32_bf16 v[58:61], v[138:141], v[172:175], v[58:61]
	v_mfma_f32_16x16x32_bf16 v[54:57], v[130:133], v[180:183], v[54:57]
	v_mfma_f32_16x16x32_bf16 v[42:45], v[138:141], v[180:183], v[42:45]
	v_mfma_f32_16x16x32_bf16 v[38:41], v[130:133], v[188:191], v[38:41]
	v_mfma_f32_16x16x32_bf16 v[26:29], v[138:141], v[188:191], v[26:29]
	v_mfma_f32_16x16x32_bf16 v[18:21], v[130:133], v[206:209], v[18:21]
	v_mfma_f32_16x16x32_bf16 v[10:13], v[138:141], v[206:209], v[10:13]
	v_mfma_f32_16x16x32_bf16 v[62:65], v[134:137], v[176:179], v[62:65]
	v_mfma_f32_16x16x32_bf16 v[58:61], v[148:151], v[176:179], v[58:61]
	v_mfma_f32_16x16x32_bf16 v[54:57], v[134:137], v[184:187], v[54:57]
	v_mfma_f32_16x16x32_bf16 v[42:45], v[148:151], v[184:187], v[42:45]
	v_mfma_f32_16x16x32_bf16 v[38:41], v[134:137], v[192:195], v[38:41]
	v_mfma_f32_16x16x32_bf16 v[26:29], v[148:151], v[192:195], v[26:29]
	v_mfma_f32_16x16x32_bf16 v[18:21], v[134:137], v[210:213], v[18:21]
	v_mfma_f32_16x16x32_bf16 v[10:13], v[148:151], v[210:213], v[10:13]
	v_mfma_f32_16x16x32_bf16 v[50:53], v[156:159], v[172:175], v[50:53]
	v_mfma_f32_16x16x32_bf16 v[46:49], v[164:167], v[172:175], v[46:49]
	v_mfma_f32_16x16x32_bf16 v[34:37], v[156:159], v[180:183], v[34:37]
	v_mfma_f32_16x16x32_bf16 v[30:33], v[164:167], v[180:183], v[30:33]
	v_mfma_f32_16x16x32_bf16 v[22:25], v[156:159], v[188:191], v[22:25]
	v_mfma_f32_16x16x32_bf16 v[14:17], v[164:167], v[188:191], v[14:17]
	v_mfma_f32_16x16x32_bf16 v[6:9], v[156:159], v[206:209], v[6:9]
	v_mfma_f32_16x16x32_bf16 v[2:5], v[164:167], v[206:209], v[2:5]
	v_mfma_f32_16x16x32_bf16 v[50:53], v[160:163], v[176:179], v[50:53]
	v_mfma_f32_16x16x32_bf16 v[46:49], v[168:171], v[176:179], v[46:49]
	v_mfma_f32_16x16x32_bf16 v[34:37], v[160:163], v[184:187], v[34:37]
	v_mfma_f32_16x16x32_bf16 v[30:33], v[168:171], v[184:187], v[30:33]
	v_mfma_f32_16x16x32_bf16 v[22:25], v[160:163], v[192:195], v[22:25]
	v_mfma_f32_16x16x32_bf16 v[14:17], v[168:171], v[192:195], v[14:17]
	v_mfma_f32_16x16x32_bf16 v[6:9], v[160:163], v[210:213], v[6:9]
	v_mfma_f32_16x16x32_bf16 v[2:5], v[168:171], v[210:213], v[2:5]
	s_setprio 0
	s_barrier
	s_add_i32 s73, s73, 2
	s_add_u32 s8, s8, 0x100
	s_addc_u32 s9, s9, 0
	s_add_u32 s58, s58, 0x100
	s_addc_u32 s72, s72, 0
	s_cmp_gt_u32 s73, 13
	s_cbranch_scc0 .LBB0_351
	s_and_b64 vcc, exec, s[10:11]
	s_cbranch_vccz .LBB0_354
	s_barrier
